# ssd xdt loop: both trips' global loads issued before the first wait; dn KK/QK epilogue: 32 conditional serialized ds_read_b32 of sGc/sBeta replaced by two ds_read_b128 preloads
# speedup vs baseline: 1.0110x; 1.0110x over previous
.LBB0_532:
	v_ashrrev_i32_e32 v7, 3, v6
	v_sub_u32_e32 v8, 63, v7
	v_cndmask_b32_e64 v8, v8, v7, s[0:1]
	v_add_u32_e32 v8, s9, v8
	v_ashrrev_i32_e32 v9, 31, v8
	v_lshlrev_b64 v[8:9], 9, v[8:9]
	s_waitcnt vmcnt(8)
	v_and_b32_e32 v12, 56, v5
	v_lshl_add_u64 v[8:9], s[4:5], 0, v[8:9]
	v_lshlrev_b32_e32 v136, 1, v12
	v_lshl_add_u64 v[8:9], v[8:9], 0, v[136:137]
	global_load_dwordx4 v[8:11], v[8:9], off
	v_add_u32_e32 v204, 32, v7
	v_sub_u32_e32 v205, 63, v204
	v_cndmask_b32_e64 v205, v205, v204, s[0:1]
	v_add_u32_e32 v206, s9, v205
	v_ashrrev_i32_e32 v207, 31, v206
	v_lshlrev_b64 v[206:207], 9, v[206:207]
	v_lshl_add_u64 v[206:207], s[4:5], 0, v[206:207]
	v_lshl_add_u64 v[206:207], v[206:207], 0, v[136:137]
	global_load_dwordx4 v[208:211], v[206:207], off
	v_lshlrev_b32_e32 v213, 2, v204
	ds_read_b32 v213, v213 offset:62720
	v_lshlrev_b32_e32 v212, 1, v204
	v_mad_u32_u24 v212, v12, s12, v212
	v_lshlrev_b32_e32 v13, 2, v7
	ds_read_b32 v13, v13 offset:62720
	v_lshlrev_b32_e32 v7, 1, v7
	v_mad_u32_u24 v7, v12, s12, v7
	s_waitcnt vmcnt(1)
	v_lshlrev_b32_e32 v14, 16, v8
	v_and_b32_e32 v8, 0xffff0000, v8
	s_waitcnt lgkmcnt(0)
	v_mul_f32_e32 v8, v13, v8
	v_cvt_pk_bf16_f32 v8, v8, s0
	ds_write_b16 v7, v8 offset:34960
	v_lshlrev_b32_e32 v8, 16, v9
	v_mul_f32_e32 v8, v13, v8
	v_cvt_pk_bf16_f32 v8, v8, s0
	ds_write_b16 v7, v8 offset:35104
	v_and_b32_e32 v8, 0xffff0000, v9
	v_mul_f32_e32 v8, v13, v8
	v_cvt_pk_bf16_f32 v8, v8, s0
	ds_write_b16 v7, v8 offset:35248
	v_lshlrev_b32_e32 v8, 16, v10
	v_mul_f32_e32 v8, v13, v8
	v_cvt_pk_bf16_f32 v8, v8, s0
	ds_write_b16 v7, v8 offset:35392
	v_and_b32_e32 v8, 0xffff0000, v10
	v_mul_f32_e32 v8, v13, v8
	v_cvt_pk_bf16_f32 v8, v8, s0
	ds_write_b16 v7, v8 offset:35536
	v_lshlrev_b32_e32 v8, 16, v11
	v_mul_f32_e32 v8, v13, v8
	v_cvt_pk_bf16_f32 v8, v8, s0
	ds_write_b16 v7, v8 offset:35680
	v_and_b32_e32 v8, 0xffff0000, v11
	v_mul_f32_e32 v14, v13, v14
	v_mul_f32_e32 v8, v13, v8
	v_cvt_pk_bf16_f32 v14, v14, s0
	v_cvt_pk_bf16_f32 v8, v8, s0
	ds_write_b16 v7, v14 offset:34816
	ds_write_b16 v7, v8 offset:35824
	s_waitcnt vmcnt(0)
	v_lshlrev_b32_e32 v214, 16, v208
	v_and_b32_e32 v208, 0xffff0000, v208
	s_waitcnt lgkmcnt(0)
	v_mul_f32_e32 v208, v213, v208
	v_cvt_pk_bf16_f32 v208, v208, s0
	ds_write_b16 v212, v208 offset:34960
	v_lshlrev_b32_e32 v208, 16, v209
	v_mul_f32_e32 v208, v213, v208
	v_cvt_pk_bf16_f32 v208, v208, s0
	ds_write_b16 v212, v208 offset:35104
	v_and_b32_e32 v208, 0xffff0000, v209
	v_mul_f32_e32 v208, v213, v208
	v_cvt_pk_bf16_f32 v208, v208, s0
	ds_write_b16 v212, v208 offset:35248
	v_lshlrev_b32_e32 v208, 16, v210
	v_mul_f32_e32 v208, v213, v208
	v_cvt_pk_bf16_f32 v208, v208, s0
	ds_write_b16 v212, v208 offset:35392
	v_and_b32_e32 v208, 0xffff0000, v210
	v_mul_f32_e32 v208, v213, v208
	v_cvt_pk_bf16_f32 v208, v208, s0
	ds_write_b16 v212, v208 offset:35536
	v_lshlrev_b32_e32 v208, 16, v211
	v_mul_f32_e32 v208, v213, v208
	v_cvt_pk_bf16_f32 v208, v208, s0
	ds_write_b16 v212, v208 offset:35680
	v_and_b32_e32 v208, 0xffff0000, v211
	v_mul_f32_e32 v214, v213, v214
	v_mul_f32_e32 v208, v213, v208
	v_cvt_pk_bf16_f32 v214, v214, s0
	v_cvt_pk_bf16_f32 v208, v208, s0
	ds_write_b16 v212, v214 offset:34816
	ds_write_b16 v212, v208 offset:35824
	v_add_u32_e32 v5, 0x1000, v5
	v_add_u32_e32 v6, 0x200, v6

.LBB0_581:
	s_or_b64 exec, exec, s[2:3]
	s_waitcnt vmcnt(9)
	v_ashrrev_i32_e32 v16, 2, v74
	v_and_b32_e32 v28, 15, v74
	v_bfi_b32 v0, -16, v16, v74
	v_and_b32_e32 v24, 48, v74
	s_movk_i32 s2, 0x90
	v_lshrrev_b32_e32 v76, 2, v74
	s_waitcnt lgkmcnt(0)
	v_mad_u64_u32 v[0:1], s[0:1], v0, s2, v[24:25]
	v_and_b32_e32 v17, 12, v76
	v_mad_u32_u24 v26, v28, s2, v24
	ds_read_b128 v[4:7], v0 offset:9216
	s_waitcnt vmcnt(8)
	ds_read_b128 v[12:15], v0
	ds_read_b128 v[8:11], v0 offset:9280
	ds_read_b128 v[0:3], v0 offset:64
	v_and_or_b32 v27, v16, -16, v17
	ds_read_b128 v[16:19], v26 offset:9216
	ds_read_b128 v[30:33], v26 offset:9280
	s_waitcnt vmcnt(2) lgkmcnt(1)
	v_mfma_f32_16x16x32_bf16 v[20:23], v[4:7], v[16:19], 0
	v_cmp_ge_i32_e64 s[0:1], v27, v28
	v_mov_b32_e32 v29, 0
	v_lshlrev_b32_e32 v26, 2, v27
	ds_read_b128 v[204:207], v26 offset:60416
	ds_read_b128 v[208:211], v26 offset:60672
	v_mfma_f32_16x16x32_bf16 v[16:19], v[12:15], v[16:19], 0
	s_waitcnt lgkmcnt(0)
	v_mfma_f32_16x16x32_bf16 v[20:23], v[8:11], v[30:33], v[20:23]
	v_mfma_f32_16x16x32_bf16 v[16:19], v[0:3], v[30:33], v[16:19]
	v_lshlrev_b32_e32 v31, 2, v28
	ds_read_b32 v37, v31 offset:60416
	v_mov_b32_e32 v30, 0
	s_and_saveexec_b64 s[2:3], s[0:1]
	s_cbranch_execz .LBB0_583
	v_mov_b32_e32 v30, v204
	s_waitcnt lgkmcnt(0)
	v_sub_f32_e32 v30, v30, v37
	v_mul_f32_e32 v30, 0x3fb8aa3b, v30
	v_exp_f32_e32 v30, v30
.LBB0_583:
	s_or_b64 exec, exec, s[2:3]
	v_cmp_gt_i32_e64 s[38:39], v27, v28
	v_mov_b32_e32 v34, 0
	s_and_saveexec_b64 s[2:3], s[38:39]
	s_cbranch_execz .LBB0_585
	v_mov_b32_e32 v32, v208
	s_waitcnt lgkmcnt(0)
	v_mul_f32_e32 v20, v20, v32
	v_mul_f32_e32 v34, v30, v20
.LBB0_585:
	s_or_b64 exec, exec, s[2:3]
	v_and_b32_e32 v32, 48, v31
	v_and_b32_e32 v20, 3, v74
	v_lshl_or_b32 v33, v27, 8, v31
	v_lshl_or_b32 v20, v20, 1, v32
	ds_write_b32 v33, v34 offset:27648
	v_mul_f32_e32 v16, v16, v30
	v_or_b32_e32 v34, 1, v27
	v_cvt_pk_bf16_f32 v16, v16, s0
	v_lshl_or_b32 v38, v27, 7, v20
	v_cmp_ge_i32_e64 s[38:39], v34, v28
	ds_write_b16 v38, v16 offset:44032
	s_and_saveexec_b64 s[2:3], s[38:39]
	s_cbranch_execz .LBB0_587
	v_mov_b32_e32 v16, v205
	s_waitcnt lgkmcnt(0)
	v_sub_f32_e32 v16, v16, v37
	v_mul_f32_e32 v16, 0x3fb8aa3b, v16
	v_exp_f32_e32 v29, v16
.LBB0_587:
	s_or_b64 exec, exec, s[2:3]
	v_mov_b32_e32 v30, 0
	v_mov_b32_e32 v16, 0
	s_and_saveexec_b64 s[2:3], s[0:1]
	s_cbranch_execz .LBB0_589
	v_mov_b32_e32 v16, v209
	s_waitcnt lgkmcnt(0)
	v_mul_f32_e32 v16, v21, v16
	v_mul_f32_e32 v16, v29, v16
.LBB0_589:
	s_or_b64 exec, exec, s[2:3]
	v_lshl_or_b32 v35, v34, 8, v31
	ds_write_b32 v35, v16 offset:27648
	v_mul_f32_e32 v16, v17, v29
	v_or_b32_e32 v29, 2, v27
	v_cvt_pk_bf16_f32 v16, v16, s0
	v_lshl_or_b32 v39, v34, 7, v20
	v_cmp_ge_i32_e64 s[0:1], v29, v28
	ds_write_b16 v39, v16 offset:44032
	s_and_saveexec_b64 s[2:3], s[0:1]
	s_cbranch_execz .LBB0_591
	v_mov_b32_e32 v16, v206
	s_waitcnt lgkmcnt(0)
	v_sub_f32_e32 v16, v16, v37
	v_mul_f32_e32 v16, 0x3fb8aa3b, v16
	v_exp_f32_e32 v30, v16
.LBB0_591:
	s_or_b64 exec, exec, s[2:3]
	v_cmp_gt_i32_e64 s[0:1], v29, v28
	v_mov_b32_e32 v16, 0
	v_mov_b32_e32 v17, 0
	s_and_saveexec_b64 s[2:3], s[0:1]
	s_cbranch_execz .LBB0_593
	v_mov_b32_e32 v17, v210
	s_waitcnt lgkmcnt(0)
	v_mul_f32_e32 v17, v22, v17
	v_mul_f32_e32 v17, v30, v17
.LBB0_593:
	s_or_b64 exec, exec, s[2:3]
	v_lshl_or_b32 v36, v29, 8, v31
	ds_write_b32 v36, v17 offset:27648
	v_mul_f32_e32 v17, v18, v30
	v_or_b32_e32 v30, 3, v27
	v_cvt_pk_bf16_f32 v17, v17, s0
	v_lshl_or_b32 v40, v29, 7, v20
	v_cmp_ge_i32_e64 s[0:1], v30, v28
	ds_write_b16 v40, v17 offset:44032
	s_and_saveexec_b64 s[2:3], s[0:1]
	s_cbranch_execz .LBB0_595
	v_mov_b32_e32 v16, v207
	s_waitcnt lgkmcnt(0)
	v_sub_f32_e32 v16, v16, v37
	v_mul_f32_e32 v16, 0x3fb8aa3b, v16
	v_exp_f32_e32 v16, v16
.LBB0_595:
	s_or_b64 exec, exec, s[2:3]
	v_cmp_gt_i32_e64 s[0:1], v30, v28
	v_mov_b32_e32 v44, 0
	v_mov_b32_e32 v17, 0
	s_and_saveexec_b64 s[2:3], s[0:1]
	s_cbranch_execz .LBB0_597
	v_mov_b32_e32 v17, v211
	s_waitcnt lgkmcnt(0)
	v_mul_f32_e32 v17, v23, v17
	v_mul_f32_e32 v17, v16, v17
.LBB0_597:
	s_or_b64 exec, exec, s[2:3]
	v_mul_f32_e32 v16, v19, v16
	v_mul_u32_u24_e32 v18, 0x90, v28
	s_waitcnt lgkmcnt(6)
	v_lshl_or_b32 v37, v30, 8, v31
	v_cvt_pk_bf16_f32 v16, v16, s0
	v_lshl_or_b32 v41, v30, 7, v20
	ds_write_b32 v37, v17 offset:27648
	ds_write_b16 v41, v16 offset:44032
	v_add_u32_e32 v24, v18, v24
	ds_read_b128 v[16:19], v24 offset:11520
	ds_read_b128 v[46:49], v24 offset:11584
	s_waitcnt lgkmcnt(1)
	v_mfma_f32_16x16x32_bf16 v[20:23], v[4:7], v[16:19], 0
	ds_read_b32 v43, v31 offset:60480
	v_or_b32_e32 v42, 16, v28
	v_cmp_ge_i32_e64 s[0:1], v27, v42
	v_mfma_f32_16x16x32_bf16 v[16:19], v[12:15], v[16:19], 0
	s_waitcnt lgkmcnt(1)
	v_mfma_f32_16x16x32_bf16 v[20:23], v[8:11], v[46:49], v[20:23]
	v_mfma_f32_16x16x32_bf16 v[16:19], v[0:3], v[46:49], v[16:19]
	s_and_saveexec_b64 s[2:3], s[0:1]
	s_cbranch_execz .LBB0_599
	v_mov_b32_e32 v44, v204
	s_waitcnt lgkmcnt(0)
	v_sub_f32_e32 v44, v44, v43
	v_mul_f32_e32 v44, 0x3fb8aa3b, v44
	v_exp_f32_e32 v44, v44
.LBB0_599:
	s_or_b64 exec, exec, s[2:3]
	v_cmp_gt_i32_e64 s[38:39], v27, v42
	v_mov_b32_e32 v45, 0
	v_mov_b32_e32 v46, 0
	s_and_saveexec_b64 s[2:3], s[38:39]
	s_cbranch_execz .LBB0_601
	v_mov_b32_e32 v46, v208
	s_waitcnt lgkmcnt(0)
	v_mul_f32_e32 v20, v20, v46
	v_mul_f32_e32 v46, v44, v20
.LBB0_601:
	s_or_b64 exec, exec, s[2:3]
	v_mul_f32_e32 v16, v16, v44
	v_cvt_pk_bf16_f32 v16, v16, s0
	v_cmp_ge_i32_e64 s[38:39], v34, v42
	ds_write_b32 v33, v46 offset:27712
	ds_write_b16 v38, v16 offset:44040
	s_and_saveexec_b64 s[2:3], s[38:39]
	s_cbranch_execz .LBB0_603
	v_mov_b32_e32 v16, v205
	s_waitcnt lgkmcnt(0)
	v_sub_f32_e32 v16, v16, v43
	v_mul_f32_e32 v16, 0x3fb8aa3b, v16
	v_exp_f32_e32 v45, v16
.LBB0_603:
	s_or_b64 exec, exec, s[2:3]
	v_mov_b32_e32 v16, 0
	v_mov_b32_e32 v20, 0
	s_and_saveexec_b64 s[2:3], s[0:1]
	s_cbranch_execz .LBB0_605
	v_mov_b32_e32 v20, v209
	s_waitcnt lgkmcnt(0)
	v_mul_f32_e32 v20, v21, v20
	v_mul_f32_e32 v20, v45, v20
.LBB0_605:
	s_or_b64 exec, exec, s[2:3]
	v_mul_f32_e32 v17, v17, v45
	v_cvt_pk_bf16_f32 v17, v17, s0
	v_cmp_ge_i32_e64 s[0:1], v29, v42
	ds_write_b32 v35, v20 offset:27712
	ds_write_b16 v39, v17 offset:44040
	s_and_saveexec_b64 s[2:3], s[0:1]
	s_cbranch_execz .LBB0_607
	v_mov_b32_e32 v16, v206
	s_waitcnt lgkmcnt(0)
	v_sub_f32_e32 v16, v16, v43
	v_mul_f32_e32 v16, 0x3fb8aa3b, v16
	v_exp_f32_e32 v16, v16
.LBB0_607:
	s_or_b64 exec, exec, s[2:3]
	v_cmp_gt_i32_e64 s[0:1], v29, v42
	v_mov_b32_e32 v17, 0
	v_mov_b32_e32 v20, 0
	s_and_saveexec_b64 s[2:3], s[0:1]
	s_cbranch_execz .LBB0_609
	v_mov_b32_e32 v20, v210
	s_waitcnt lgkmcnt(0)
	v_mul_f32_e32 v20, v22, v20
	v_mul_f32_e32 v20, v16, v20
.LBB0_609:
	s_or_b64 exec, exec, s[2:3]
	v_mul_f32_e32 v16, v18, v16
	v_cvt_pk_bf16_f32 v16, v16, s0
	v_cmp_ge_i32_e64 s[0:1], v30, v42
	ds_write_b32 v36, v20 offset:27712
	ds_write_b16 v40, v16 offset:44040
	s_and_saveexec_b64 s[2:3], s[0:1]
	s_cbranch_execz .LBB0_611
	v_mov_b32_e32 v16, v207
	s_waitcnt lgkmcnt(0)
	v_sub_f32_e32 v16, v16, v43
	v_mul_f32_e32 v16, 0x3fb8aa3b, v16
	v_exp_f32_e32 v17, v16
.LBB0_611:
	s_or_b64 exec, exec, s[2:3]
	v_cmp_gt_i32_e64 s[0:1], v30, v42
	v_mov_b32_e32 v42, 0
	v_mov_b32_e32 v16, 0
	s_and_saveexec_b64 s[2:3], s[0:1]
	s_cbranch_execz .LBB0_613
	v_mov_b32_e32 v16, v211
	s_waitcnt lgkmcnt(0)
	v_mul_f32_e32 v16, v23, v16
	v_mul_f32_e32 v16, v17, v16
.LBB0_613:
	s_or_b64 exec, exec, s[2:3]
	ds_write_b32 v37, v16 offset:27712
	v_mul_f32_e32 v16, v19, v17
	v_cvt_pk_bf16_f32 v16, v16, s0
	ds_write_b16 v41, v16 offset:44040
	ds_read_b128 v[16:19], v24 offset:13824
	ds_read_b128 v[44:47], v24 offset:13888
	ds_read_b32 v39, v31 offset:60544
	v_or_b32_e32 v38, 32, v28
	s_waitcnt lgkmcnt(2)
	v_mfma_f32_16x16x32_bf16 v[20:23], v[4:7], v[16:19], 0
	v_cmp_ge_i32_e64 s[0:1], v27, v38
	v_mfma_f32_16x16x32_bf16 v[16:19], v[12:15], v[16:19], 0
	s_waitcnt lgkmcnt(1)
	v_mfma_f32_16x16x32_bf16 v[20:23], v[8:11], v[44:47], v[20:23]
	v_mfma_f32_16x16x32_bf16 v[16:19], v[0:3], v[44:47], v[16:19]
	s_and_saveexec_b64 s[2:3], s[0:1]
	s_cbranch_execz .LBB0_615
	v_mov_b32_e32 v40, v204
	s_waitcnt lgkmcnt(0)
	v_sub_f32_e32 v40, v40, v39
	v_mul_f32_e32 v40, 0x3fb8aa3b, v40
	v_exp_f32_e32 v42, v40
.LBB0_615:
	s_or_b64 exec, exec, s[2:3]
	v_cmp_gt_i32_e64 s[38:39], v27, v38
	v_mov_b32_e32 v41, 0
	v_mov_b32_e32 v43, 0
	s_and_saveexec_b64 s[2:3], s[38:39]
	s_cbranch_execz .LBB0_617
	v_mov_b32_e32 v40, v208
	s_waitcnt lgkmcnt(0)
	v_mul_f32_e32 v20, v20, v40
	v_mul_f32_e32 v43, v42, v20
.LBB0_617:
	s_or_b64 exec, exec, s[2:3]
	v_and_b32_e32 v40, 35, v38
	v_lshlrev_b32_e32 v20, 6, v27
	v_lshl_add_u32 v40, v40, 1, v32
	v_mul_f32_e32 v16, v16, v42
	v_cvt_pk_bf16_f32 v16, v16, s0
	v_lshl_add_u32 v42, v20, 1, v40
	v_cmp_ge_i32_e64 s[38:39], v34, v38
	ds_write_b32 v33, v43 offset:27776
	ds_write_b16 v42, v16 offset:44032
	s_and_saveexec_b64 s[2:3], s[38:39]
	s_cbranch_execz .LBB0_619
	v_mov_b32_e32 v16, v205
	s_waitcnt lgkmcnt(0)
	v_sub_f32_e32 v16, v16, v39
	v_mul_f32_e32 v16, 0x3fb8aa3b, v16
	v_exp_f32_e32 v41, v16
.LBB0_619:
	s_or_b64 exec, exec, s[2:3]
	v_mov_b32_e32 v42, 0
	v_mov_b32_e32 v43, 0
	s_and_saveexec_b64 s[2:3], s[0:1]
	s_cbranch_execz .LBB0_621
	v_mov_b32_e32 v16, v209
	s_waitcnt lgkmcnt(0)
	v_mul_f32_e32 v16, v21, v16
	v_mul_f32_e32 v43, v41, v16
.LBB0_621:
	s_or_b64 exec, exec, s[2:3]
	v_lshlrev_b32_e32 v16, 6, v34
	v_mul_f32_e32 v17, v17, v41
	v_cvt_pk_bf16_f32 v17, v17, s0
	v_lshl_add_u32 v21, v16, 1, v40
	v_cmp_ge_i32_e64 s[0:1], v29, v38
	ds_write_b32 v35, v43 offset:27776
	ds_write_b16 v21, v17 offset:44032
	s_and_saveexec_b64 s[2:3], s[0:1]
	s_cbranch_execz .LBB0_623
	v_mov_b32_e32 v17, v206
	s_waitcnt lgkmcnt(0)
	v_sub_f32_e32 v17, v17, v39
	v_mul_f32_e32 v17, 0x3fb8aa3b, v17
	v_exp_f32_e32 v42, v17
.LBB0_623:
	s_or_b64 exec, exec, s[2:3]
	v_cmp_gt_i32_e64 s[0:1], v29, v38
	v_mov_b32_e32 v41, 0
	v_mov_b32_e32 v21, 0
	s_and_saveexec_b64 s[2:3], s[0:1]
	s_cbranch_execz .LBB0_625
	v_mov_b32_e32 v17, v210
	s_waitcnt lgkmcnt(0)
	v_mul_f32_e32 v17, v22, v17
	v_mul_f32_e32 v21, v42, v17
.LBB0_625:
	s_or_b64 exec, exec, s[2:3]
	v_lshlrev_b32_e32 v17, 6, v29
	v_mul_f32_e32 v18, v18, v42
	ds_write_b32 v36, v21 offset:27776
	v_cvt_pk_bf16_f32 v18, v18, s0
	v_lshl_add_u32 v21, v17, 1, v40
	v_cmp_ge_i32_e64 s[0:1], v30, v38
	ds_write_b16 v21, v18 offset:44032
	s_and_saveexec_b64 s[2:3], s[0:1]
	s_cbranch_execz .LBB0_627
	v_mov_b32_e32 v18, v207
	s_waitcnt lgkmcnt(0)
	v_sub_f32_e32 v18, v18, v39
	v_mul_f32_e32 v18, 0x3fb8aa3b, v18
	v_exp_f32_e32 v41, v18
.LBB0_627:
	s_or_b64 exec, exec, s[2:3]
	v_cmp_gt_i32_e64 s[0:1], v30, v38
	v_mov_b32_e32 v21, 0
	v_mov_b32_e32 v22, 0
	s_and_saveexec_b64 s[2:3], s[0:1]
	s_cbranch_execz .LBB0_629
	v_mov_b32_e32 v18, v211
	s_waitcnt lgkmcnt(0)
	v_mul_f32_e32 v18, v23, v18
	v_mul_f32_e32 v22, v41, v18
.LBB0_629:
	s_or_b64 exec, exec, s[2:3]
	v_lshlrev_b32_e32 v18, 6, v30
	v_mul_f32_e32 v19, v19, v41
	ds_write_b32 v37, v22 offset:27776
	v_cvt_pk_bf16_f32 v19, v19, s0
	v_lshl_add_u32 v22, v18, 1, v40
	ds_write_b16 v22, v19 offset:44032
	s_waitcnt lgkmcnt(8)
	ds_read_b128 v[38:41], v24 offset:16128
	ds_read_b32 v19, v31 offset:60608
	s_waitcnt lgkmcnt(1)
	v_mfma_f32_16x16x32_bf16 v[4:7], v[4:7], v[38:41], 0
	v_mfma_f32_16x16x32_bf16 v[12:15], v[12:15], v[38:41], 0
	ds_read_b128 v[38:41], v24 offset:16192
	s_waitcnt lgkmcnt(0)
	v_mfma_f32_16x16x32_bf16 v[4:7], v[8:11], v[38:41], v[4:7]
	v_or_b32_e32 v8, 48, v28
	v_cmp_ge_i32_e64 s[0:1], v27, v8
	v_mfma_f32_16x16x32_bf16 v[0:3], v[0:3], v[38:41], v[12:15]
	s_and_saveexec_b64 s[2:3], s[0:1]
	s_cbranch_execz .LBB0_631
	v_mov_b32_e32 v9, v204
	s_waitcnt lgkmcnt(0)
	v_sub_f32_e32 v9, v9, v19
	v_mul_f32_e32 v9, 0x3fb8aa3b, v9
	v_exp_f32_e32 v21, v9
.LBB0_631:
	s_or_b64 exec, exec, s[2:3]
	v_cmp_gt_i32_e64 s[38:39], v27, v8
	v_mov_b32_e32 v9, 0
	v_mov_b32_e32 v10, 0
	s_and_saveexec_b64 s[2:3], s[38:39]
	s_cbranch_execz .LBB0_633
	v_mov_b32_e32 v10, v208
	s_waitcnt lgkmcnt(0)
	v_mul_f32_e32 v4, v4, v10
	v_mul_f32_e32 v10, v21, v4
.LBB0_633:
	s_or_b64 exec, exec, s[2:3]
	v_and_b32_e32 v4, 35, v8
	v_lshl_add_u32 v4, v4, 1, v32
	v_mul_f32_e32 v0, v0, v21
	ds_write_b32 v33, v10 offset:27840
	v_cvt_pk_bf16_f32 v0, v0, s0
	v_lshl_add_u32 v10, v20, 1, v4
	v_cmp_ge_i32_e64 s[38:39], v34, v8
	ds_write_b16 v10, v0 offset:44040
	s_and_saveexec_b64 s[2:3], s[38:39]
	s_cbranch_execz .LBB0_635
	v_mov_b32_e32 v0, v205
	s_waitcnt lgkmcnt(0)
	v_sub_f32_e32 v0, v0, v19
	v_mul_f32_e32 v0, 0x3fb8aa3b, v0
	v_exp_f32_e32 v9, v0
.LBB0_635:
	s_or_b64 exec, exec, s[2:3]
	v_mov_b32_e32 v0, 0
	v_mov_b32_e32 v10, 0
	s_and_saveexec_b64 s[2:3], s[0:1]
	s_cbranch_execz .LBB0_637
	v_mov_b32_e32 v10, v209
	s_waitcnt lgkmcnt(0)
	v_mul_f32_e32 v5, v5, v10
	v_mul_f32_e32 v10, v9, v5
.LBB0_637:
	s_or_b64 exec, exec, s[2:3]
	v_mul_f32_e32 v1, v1, v9
	v_cvt_pk_bf16_f32 v1, v1, s0
	v_lshl_add_u32 v5, v16, 1, v4
	v_cmp_ge_i32_e64 s[0:1], v29, v8
	ds_write_b32 v35, v10 offset:27840
	ds_write_b16 v5, v1 offset:44040
	s_and_saveexec_b64 s[2:3], s[0:1]
	s_cbranch_execz .LBB0_639
	v_mov_b32_e32 v0, v206
	s_waitcnt lgkmcnt(0)
	v_sub_f32_e32 v0, v0, v19
	v_mul_f32_e32 v0, 0x3fb8aa3b, v0
	v_exp_f32_e32 v0, v0
.LBB0_639:
	s_or_b64 exec, exec, s[2:3]
	v_cmp_gt_i32_e64 s[0:1], v29, v8
	v_mov_b32_e32 v1, 0
	v_mov_b32_e32 v5, 0
	s_and_saveexec_b64 s[2:3], s[0:1]
	s_cbranch_execz .LBB0_641
	v_mov_b32_e32 v5, v210
	s_waitcnt lgkmcnt(0)
	v_mul_f32_e32 v5, v6, v5
	v_mul_f32_e32 v5, v0, v5
.LBB0_641:
	s_or_b64 exec, exec, s[2:3]
	v_mul_f32_e32 v0, v2, v0
	v_cvt_pk_bf16_f32 v0, v0, s0
	v_lshl_add_u32 v2, v17, 1, v4
	v_cmp_ge_i32_e64 s[0:1], v30, v8
	ds_write_b32 v36, v5 offset:27840
	ds_write_b16 v2, v0 offset:44040
	s_and_saveexec_b64 s[2:3], s[0:1]
	s_cbranch_execz .LBB0_643
	v_mov_b32_e32 v0, v207
	s_waitcnt lgkmcnt(0)
	v_sub_f32_e32 v0, v0, v19
	v_mul_f32_e32 v0, 0x3fb8aa3b, v0
	v_exp_f32_e32 v1, v0
.LBB0_643:
	s_or_b64 exec, exec, s[2:3]
	v_cmp_gt_i32_e64 s[0:1], v30, v8
	v_mov_b32_e32 v0, 0
	s_and_saveexec_b64 s[2:3], s[0:1]
	s_cbranch_execz .LBB0_645
	v_mov_b32_e32 v0, v211
	s_waitcnt lgkmcnt(0)
	v_mul_f32_e32 v0, v7, v0
	v_mul_f32_e32 v0, v1, v0
